# in-proj epilogue: K (fragment-major) stores widened to dwordx4 by exchanging 8-byte halves between lane pairs with v_permlane16_swap
# baseline (speedup 1.0000x reference)
; DI u32x2 pk4(f32x4 v) { u32x2 r; r.x = pk2(v[0], v[1]); r.y = pk2(v[2], v[3]); return r; }
; DI size_t kf_off(int h, int nblk, int krow, int d) { return ((((size_t)h * nblk + (krow >> 5)) * 4 + (d >> 4)) * 64 + ((d >> 3) & 1) * 32 + (krow & 31)) * 8 + (d & 7); }
;     DI void operator()(const AccT& acc, const Unit& u, int wr, int wc, int fr, int fq, LAS unsigned char*) const {
;     ...
;                     if (isK) {
;                         bf16_t* kp = (bf16_t*)(ws + (isA ? WS_KA : WS_KB));
; #pragma unroll
;                         for (int bj = 0; bj < 2; ++bj)
; #pragma unroll
;                             for (int n = 0; n < 2; ++n) *(u32x2*)(kp + kf_off(h, krows >> 5, krow, 32 * bj + 16 * n + 4 * fq)) = pk4(v[bj][n]);
.LBB0_176:
	s_and_b64 vcc, exec, s[10:11]
	s_cbranch_vccz .LBB0_178
	v_lshl_add_u64 v[184:185], s[46:47], 0, v[184:185]
	v_lshlrev_b64 v[184:185], 8, v[184:185]
	v_and_or_b32 v150, v183, 15, v184
	v_lshl_add_u64 v[186:187], v[170:171], 0, s[48:49]
	v_or_b32_e32 v184, v150, v144
	v_lshl_add_u64 v[184:185], v[184:185], 4, v[186:187]
	s_waitcnt lgkmcnt(0)
	v_and_b32_e32 v186, 16, v226
	v_lshlrev_b32_e32 v187, 6, v186
	v_lshrrev_b32_e32 v186, 1, v186
	v_sub_u32_e32 v150, v187, v186
	v_lshl_add_u64 v[184:185], v[184:185], 0, v[150:151]
	v_cvt_pk_bf16_f32 v140, v140, v141
	v_cvt_pk_bf16_f32 v141, v142, v143
	v_cvt_pk_bf16_f32 v142, v136, v137
	v_cvt_pk_bf16_f32 v143, v138, v139
	v_cvt_pk_bf16_f32 v132, v132, v133
	v_cvt_pk_bf16_f32 v133, v134, v135
	v_cvt_pk_bf16_f32 v134, v128, v129
	v_cvt_pk_bf16_f32 v135, v130, v131
	s_nop 1
	v_permlane16_swap_b32_e32 v140, v142
	v_permlane16_swap_b32_e32 v141, v143
	v_permlane16_swap_b32_e32 v132, v134
	v_permlane16_swap_b32_e32 v133, v135
	global_store_dwordx4 v[184:185], v[140:143], off
	global_store_dwordx4 v[184:185], v[132:135], off offset:2048

; DI u32x2 pk4(f32x4 v) { u32x2 r; r.x = pk2(v[0], v[1]); r.y = pk2(v[2], v[3]); return r; }
; DI size_t kf_off(int h, int nblk, int krow, int d) { return ((((size_t)h * nblk + (krow >> 5)) * 4 + (d >> 4)) * 64 + ((d >> 3) & 1) * 32 + (krow & 31)) * 8 + (d & 7); }
;     DI void operator()(const AccT& acc, const Unit& u, int wr, int wc, int fr, int fq, LAS unsigned char*) const {
;     ...
;                     if (isK) {
;                         bf16_t* kp = (bf16_t*)(ws + (isA ? WS_KA : WS_KB));
; #pragma unroll
;                         for (int bj = 0; bj < 2; ++bj)
; #pragma unroll
;                             for (int n = 0; n < 2; ++n) *(u32x2*)(kp + kf_off(h, krows >> 5, krow, 32 * bj + 16 * n + 4 * fq)) = pk4(v[bj][n]);
.LBB0_226:
	s_and_b64 vcc, exec, s[0:1]
	s_cbranch_vccz .LBB0_228
	v_lshl_add_u64 v[130:131], s[46:47], 0, v[130:131]
	v_lshlrev_b64 v[130:131], 8, v[130:131]
	v_and_or_b32 v129, v129, 31, v130
	v_lshl_add_u64 v[132:133], v[170:171], 0, s[48:49]
	v_or_b32_e32 v130, v129, v144
	v_lshl_add_u64 v[130:131], v[130:131], 4, v[132:133]
	s_waitcnt lgkmcnt(0)
	v_and_b32_e32 v132, 16, v226
	v_lshlrev_b32_e32 v133, 6, v132
	v_lshrrev_b32_e32 v132, 1, v132
	v_sub_u32_e32 v150, v133, v132
	v_lshl_add_u64 v[130:131], v[130:131], 0, v[150:151]
	v_cvt_pk_bf16_f32 v124, v124, v125
	v_cvt_pk_bf16_f32 v125, v126, v127
	v_cvt_pk_bf16_f32 v126, v120, v121
	v_cvt_pk_bf16_f32 v127, v122, v123
	v_cvt_pk_bf16_f32 v116, v116, v117
	v_cvt_pk_bf16_f32 v117, v118, v119
	v_cvt_pk_bf16_f32 v118, v112, v113
	v_cvt_pk_bf16_f32 v119, v114, v115
	s_nop 1
	v_permlane16_swap_b32_e32 v124, v126
	v_permlane16_swap_b32_e32 v125, v127
	v_permlane16_swap_b32_e32 v116, v118
	v_permlane16_swap_b32_e32 v117, v119
	global_store_dwordx4 v[130:131], v[124:127], off
	global_store_dwordx4 v[130:131], v[116:119], off offset:2048

; DI u32x2 pk4(f32x4 v) { u32x2 r; r.x = pk2(v[0], v[1]); r.y = pk2(v[2], v[3]); return r; }
; DI size_t kf_off(int h, int nblk, int krow, int d) { return ((((size_t)h * nblk + (krow >> 5)) * 4 + (d >> 4)) * 64 + ((d >> 3) & 1) * 32 + (krow & 31)) * 8 + (d & 7); }
;     DI void operator()(const AccT& acc, const Unit& u, int wr, int wc, int fr, int fq, LAS unsigned char*) const {
;     ...
;                     if (isK) {
;                         bf16_t* kp = (bf16_t*)(ws + (isA ? WS_KA : WS_KB));
; #pragma unroll
;                         for (int bj = 0; bj < 2; ++bj)
; #pragma unroll
;                             for (int n = 0; n < 2; ++n) *(u32x2*)(kp + kf_off(h, krows >> 5, krow, 32 * bj + 16 * n + 4 * fq)) = pk4(v[bj][n]);
.LBB0_272:
	s_and_b64 vcc, exec, s[0:1]
	s_cbranch_vccz .LBB0_274
	v_lshl_add_u64 v[114:115], s[46:47], 0, v[114:115]
	v_lshlrev_b64 v[114:115], 8, v[114:115]
	v_and_or_b32 v113, v113, 15, v114
	v_lshl_add_u64 v[116:117], v[170:171], 0, s[48:49]
	v_or_b32_e32 v114, v113, v144
	v_lshl_add_u64 v[114:115], v[114:115], 4, v[116:117]
	s_waitcnt lgkmcnt(0)
	v_and_b32_e32 v116, 16, v226
	v_lshlrev_b32_e32 v117, 6, v116
	v_lshrrev_b32_e32 v116, 1, v116
	v_sub_u32_e32 v150, v117, v116
	v_lshl_add_u64 v[114:115], v[114:115], 0, v[150:151]
	v_cvt_pk_bf16_f32 v108, v108, v109
	v_cvt_pk_bf16_f32 v109, v110, v111
	v_cvt_pk_bf16_f32 v110, v104, v105
	v_cvt_pk_bf16_f32 v111, v106, v107
	v_cvt_pk_bf16_f32 v100, v100, v101
	v_cvt_pk_bf16_f32 v101, v102, v103
	v_cvt_pk_bf16_f32 v102, v96, v97
	v_cvt_pk_bf16_f32 v103, v98, v99
	s_nop 1
	v_permlane16_swap_b32_e32 v108, v110
	v_permlane16_swap_b32_e32 v109, v111
	v_permlane16_swap_b32_e32 v100, v102
	v_permlane16_swap_b32_e32 v101, v103
	global_store_dwordx4 v[114:115], v[108:111], off
	global_store_dwordx4 v[114:115], v[100:103], off offset:2048

; DI u32x2 pk4(f32x4 v) { u32x2 r; r.x = pk2(v[0], v[1]); r.y = pk2(v[2], v[3]); return r; }
; DI size_t kf_off(int h, int nblk, int krow, int d) { return ((((size_t)h * nblk + (krow >> 5)) * 4 + (d >> 4)) * 64 + ((d >> 3) & 1) * 32 + (krow & 31)) * 8 + (d & 7); }
;     DI void operator()(const AccT& acc, const Unit& u, int wr, int wc, int fr, int fq, LAS unsigned char*) const {
;     ...
;                     if (isK) {
;                         bf16_t* kp = (bf16_t*)(ws + (isA ? WS_KA : WS_KB));
; #pragma unroll
;                         for (int bj = 0; bj < 2; ++bj)
; #pragma unroll
;                             for (int n = 0; n < 2; ++n) *(u32x2*)(kp + kf_off(h, krows >> 5, krow, 32 * bj + 16 * n + 4 * fq)) = pk4(v[bj][n]);
.LBB0_318:
	s_and_b64 vcc, exec, s[0:1]
	s_cbranch_vccz .LBB0_320
	v_lshl_add_u64 v[98:99], s[46:47], 0, v[98:99]
	v_lshlrev_b64 v[98:99], 8, v[98:99]
	v_and_or_b32 v97, v97, 31, v98
	v_lshl_add_u64 v[100:101], v[170:171], 0, s[48:49]
	v_or_b32_e32 v98, v97, v144
	v_lshl_add_u64 v[98:99], v[98:99], 4, v[100:101]
	s_waitcnt lgkmcnt(0)
	v_and_b32_e32 v100, 16, v226
	v_lshlrev_b32_e32 v101, 6, v100
	v_lshrrev_b32_e32 v100, 1, v100
	v_sub_u32_e32 v150, v101, v100
	v_lshl_add_u64 v[98:99], v[98:99], 0, v[150:151]
	v_cvt_pk_bf16_f32 v92, v92, v93
	v_cvt_pk_bf16_f32 v93, v94, v95
	v_cvt_pk_bf16_f32 v94, v88, v89
	v_cvt_pk_bf16_f32 v95, v90, v91
	v_cvt_pk_bf16_f32 v84, v84, v85
	v_cvt_pk_bf16_f32 v85, v86, v87
	v_cvt_pk_bf16_f32 v86, v80, v81
	v_cvt_pk_bf16_f32 v87, v82, v83
	s_nop 1
	v_permlane16_swap_b32_e32 v92, v94
	v_permlane16_swap_b32_e32 v93, v95
	v_permlane16_swap_b32_e32 v84, v86
	v_permlane16_swap_b32_e32 v85, v87
	global_store_dwordx4 v[98:99], v[92:95], off
	global_store_dwordx4 v[98:99], v[84:87], off offset:2048

; DI u32x2 pk4(f32x4 v) { u32x2 r; r.x = pk2(v[0], v[1]); r.y = pk2(v[2], v[3]); return r; }
; DI size_t kf_off(int h, int nblk, int krow, int d) { return ((((size_t)h * nblk + (krow >> 5)) * 4 + (d >> 4)) * 64 + ((d >> 3) & 1) * 32 + (krow & 31)) * 8 + (d & 7); }
;     DI void operator()(const AccT& acc, const Unit& u, int wr, int wc, int fr, int fq, LAS unsigned char*) const {
;     ...
;                     if (isK) {
;                         bf16_t* kp = (bf16_t*)(ws + (isA ? WS_KA : WS_KB));
; #pragma unroll
;                         for (int bj = 0; bj < 2; ++bj)
; #pragma unroll
;                             for (int n = 0; n < 2; ++n) *(u32x2*)(kp + kf_off(h, krows >> 5, krow, 32 * bj + 16 * n + 4 * fq)) = pk4(v[bj][n]);
.LBB0_364:
	s_and_b64 vcc, exec, s[0:1]
	s_cbranch_vccz .LBB0_366
	v_lshl_add_u64 v[82:83], s[46:47], 0, v[82:83]
	v_lshlrev_b64 v[82:83], 8, v[82:83]
	v_and_or_b32 v81, v81, 15, v82
	v_lshl_add_u64 v[84:85], v[170:171], 0, s[48:49]
	v_or_b32_e32 v82, v81, v144
	v_lshl_add_u64 v[82:83], v[82:83], 4, v[84:85]
	s_waitcnt lgkmcnt(0)
	v_and_b32_e32 v84, 16, v226
	v_lshlrev_b32_e32 v85, 6, v84
	v_lshrrev_b32_e32 v84, 1, v84
	v_sub_u32_e32 v150, v85, v84
	v_lshl_add_u64 v[82:83], v[82:83], 0, v[150:151]
	v_cvt_pk_bf16_f32 v76, v76, v77
	v_cvt_pk_bf16_f32 v77, v78, v79
	v_cvt_pk_bf16_f32 v78, v72, v73
	v_cvt_pk_bf16_f32 v79, v74, v75
	v_cvt_pk_bf16_f32 v68, v68, v69
	v_cvt_pk_bf16_f32 v69, v70, v71
	v_cvt_pk_bf16_f32 v70, v64, v65
	v_cvt_pk_bf16_f32 v71, v66, v67
	s_nop 1
	v_permlane16_swap_b32_e32 v76, v78
	v_permlane16_swap_b32_e32 v77, v79
	v_permlane16_swap_b32_e32 v68, v70
	v_permlane16_swap_b32_e32 v69, v71
	global_store_dwordx4 v[82:83], v[76:79], off
	global_store_dwordx4 v[82:83], v[68:71], off offset:2048

; DI u32x2 pk4(f32x4 v) { u32x2 r; r.x = pk2(v[0], v[1]); r.y = pk2(v[2], v[3]); return r; }
; DI size_t kf_off(int h, int nblk, int krow, int d) { return ((((size_t)h * nblk + (krow >> 5)) * 4 + (d >> 4)) * 64 + ((d >> 3) & 1) * 32 + (krow & 31)) * 8 + (d & 7); }
;     DI void operator()(const AccT& acc, const Unit& u, int wr, int wc, int fr, int fq, LAS unsigned char*) const {
;     ...
;                     if (isK) {
;                         bf16_t* kp = (bf16_t*)(ws + (isA ? WS_KA : WS_KB));
; #pragma unroll
;                         for (int bj = 0; bj < 2; ++bj)
; #pragma unroll
;                             for (int n = 0; n < 2; ++n) *(u32x2*)(kp + kf_off(h, krows >> 5, krow, 32 * bj + 16 * n + 4 * fq)) = pk4(v[bj][n]);
.LBB0_410:
	s_and_b64 vcc, exec, s[0:1]
	s_cbranch_vccz .LBB0_412
	v_lshl_add_u64 v[66:67], s[46:47], 0, v[66:67]
	v_lshlrev_b64 v[66:67], 8, v[66:67]
	v_and_or_b32 v65, v65, 31, v66
	v_lshl_add_u64 v[68:69], v[170:171], 0, s[48:49]
	v_or_b32_e32 v66, v65, v144
	v_lshl_add_u64 v[66:67], v[66:67], 4, v[68:69]
	s_waitcnt lgkmcnt(0)
	v_and_b32_e32 v68, 16, v226
	v_lshlrev_b32_e32 v69, 6, v68
	v_lshrrev_b32_e32 v68, 1, v68
	v_sub_u32_e32 v150, v69, v68
	v_lshl_add_u64 v[66:67], v[66:67], 0, v[150:151]
	v_cvt_pk_bf16_f32 v44, v44, v45
	v_cvt_pk_bf16_f32 v45, v46, v47
	v_cvt_pk_bf16_f32 v46, v40, v41
	v_cvt_pk_bf16_f32 v47, v42, v43
	v_cvt_pk_bf16_f32 v36, v36, v37
	v_cvt_pk_bf16_f32 v37, v38, v39
	v_cvt_pk_bf16_f32 v38, v32, v33
	v_cvt_pk_bf16_f32 v39, v34, v35
	s_nop 1
	v_permlane16_swap_b32_e32 v44, v46
	v_permlane16_swap_b32_e32 v45, v47
	v_permlane16_swap_b32_e32 v36, v38
	v_permlane16_swap_b32_e32 v37, v39
	global_store_dwordx4 v[66:67], v[44:47], off
	global_store_dwordx4 v[66:67], v[36:39], off offset:2048

; DI u32x2 pk4(f32x4 v) { u32x2 r; r.x = pk2(v[0], v[1]); r.y = pk2(v[2], v[3]); return r; }
; DI size_t kf_off(int h, int nblk, int krow, int d) { return ((((size_t)h * nblk + (krow >> 5)) * 4 + (d >> 4)) * 64 + ((d >> 3) & 1) * 32 + (krow & 31)) * 8 + (d & 7); }
;     DI void operator()(const AccT& acc, const Unit& u, int wr, int wc, int fr, int fq, LAS unsigned char*) const {
;     ...
;                     if (isK) {
;                         bf16_t* kp = (bf16_t*)(ws + (isA ? WS_KA : WS_KB));
; #pragma unroll
;                         for (int bj = 0; bj < 2; ++bj)
; #pragma unroll
;                             for (int n = 0; n < 2; ++n) *(u32x2*)(kp + kf_off(h, krows >> 5, krow, 32 * bj + 16 * n + 4 * fq)) = pk4(v[bj][n]);
.LBB0_456:
	s_and_b64 vcc, exec, s[0:1]
	s_cbranch_vccz .LBB0_458
	v_lshl_add_u64 v[34:35], s[46:47], 0, v[34:35]
	v_lshlrev_b64 v[34:35], 8, v[34:35]
	v_and_or_b32 v33, v33, 15, v34
	v_lshl_add_u64 v[36:37], v[170:171], 0, s[48:49]
	v_or_b32_e32 v34, v33, v144
	v_lshl_add_u64 v[34:35], v[34:35], 4, v[36:37]
	s_waitcnt lgkmcnt(0)
	v_and_b32_e32 v36, 16, v226
	v_lshlrev_b32_e32 v37, 6, v36
	v_lshrrev_b32_e32 v36, 1, v36
	v_sub_u32_e32 v150, v37, v36
	v_lshl_add_u64 v[34:35], v[34:35], 0, v[150:151]
	v_cvt_pk_bf16_f32 v28, v28, v29
	v_cvt_pk_bf16_f32 v29, v30, v31
	v_cvt_pk_bf16_f32 v30, v24, v25
	v_cvt_pk_bf16_f32 v31, v26, v27
	v_cvt_pk_bf16_f32 v20, v20, v21
	v_cvt_pk_bf16_f32 v21, v22, v23
	v_cvt_pk_bf16_f32 v22, v16, v17
	v_cvt_pk_bf16_f32 v23, v18, v19
	s_nop 1
	v_permlane16_swap_b32_e32 v28, v30
	v_permlane16_swap_b32_e32 v29, v31
	v_permlane16_swap_b32_e32 v20, v22
	v_permlane16_swap_b32_e32 v21, v23
	global_store_dwordx4 v[34:35], v[28:31], off
	global_store_dwordx4 v[34:35], v[20:23], off offset:2048

; DI u32x2 pk4(f32x4 v) { u32x2 r; r.x = pk2(v[0], v[1]); r.y = pk2(v[2], v[3]); return r; }
; DI size_t kf_off(int h, int nblk, int krow, int d) { return ((((size_t)h * nblk + (krow >> 5)) * 4 + (d >> 4)) * 64 + ((d >> 3) & 1) * 32 + (krow & 31)) * 8 + (d & 7); }
;     DI void operator()(const AccT& acc, const Unit& u, int wr, int wc, int fr, int fq, LAS unsigned char*) const {
;     ...
;                     if (isK) {
;                         bf16_t* kp = (bf16_t*)(ws + (isA ? WS_KA : WS_KB));
; #pragma unroll
;                         for (int bj = 0; bj < 2; ++bj)
; #pragma unroll
;                             for (int n = 0; n < 2; ++n) *(u32x2*)(kp + kf_off(h, krows >> 5, krow, 32 * bj + 16 * n + 4 * fq)) = pk4(v[bj][n]);
.LBB0_502:
	s_and_b64 vcc, exec, s[0:1]
	s_cbranch_vccz .LBB0_504
	v_lshl_add_u64 v[18:19], s[46:47], 0, v[18:19]
	v_lshlrev_b64 v[18:19], 8, v[18:19]
	v_and_or_b32 v17, v17, 31, v18
	v_lshl_add_u64 v[20:21], v[170:171], 0, s[48:49]
	v_or_b32_e32 v18, v17, v144
	v_lshl_add_u64 v[18:19], v[18:19], 4, v[20:21]
	s_waitcnt lgkmcnt(0)
	v_and_b32_e32 v20, 16, v226
	v_lshlrev_b32_e32 v21, 6, v20
	v_lshrrev_b32_e32 v20, 1, v20
	v_sub_u32_e32 v150, v21, v20
	v_lshl_add_u64 v[18:19], v[18:19], 0, v[150:151]
	v_cvt_pk_bf16_f32 v12, v12, v13
	v_cvt_pk_bf16_f32 v13, v14, v15
	v_cvt_pk_bf16_f32 v14, v8, v9
	v_cvt_pk_bf16_f32 v15, v10, v11
	v_cvt_pk_bf16_f32 v4, v4, v5
	v_cvt_pk_bf16_f32 v5, v6, v7
	v_cvt_pk_bf16_f32 v6, v0, v1
	v_cvt_pk_bf16_f32 v7, v2, v3
	s_nop 1
	v_permlane16_swap_b32_e32 v12, v14
	v_permlane16_swap_b32_e32 v13, v15
	v_permlane16_swap_b32_e32 v4, v6
	v_permlane16_swap_b32_e32 v5, v7
	global_store_dwordx4 v[18:19], v[12:15], off
	global_store_dwordx4 v[18:19], v[4:7], off offset:2048
